# down-proj sample tail split into 176 K=512 units (11 bf16 partials in free YIN buffer, f32 sum in resnorm) on top of conversion loads rewrite
# speedup vs baseline: 1.0117x; 1.0117x over previous
.LBB0_778:
	s_cmpk_lg_i32 s12, 0x1600
	s_cbranch_scc1 .Lks_four
	s_cmpk_lg_i32 s38, 0x100
	s_cbranch_scc1 .Lks_four
	s_lshr_b32 s4, s2, 1
	v_writelane_b32 v248, s4, 22
	s_and_b32 s4, s2, 1
	v_writelane_b32 v248, s4, 23
	s_lshr_b32 s4, s2, 4
	v_writelane_b32 v248, s4, 24
	s_bfe_u32 s4, s2, 0x30001
	v_writelane_b32 v248, s4, 26
	s_mov_b32 s4, 0
	v_writelane_b32 v248, s4, 25
	v_writelane_b32 v248, s4, 27
	s_mov_b32 s4, 1
	v_writelane_b32 v248, s4, 28
	s_cmpk_lt_u32 s2, 0xb0
	s_cselect_b64 s[4:5], -1, 0
	s_branch .Lks_done
.Lks_four:
	v_readlane_b32 s4, v249, 44
	v_readlane_b32 s5, v249, 45
	s_nop 1
	v_writelane_b32 v248, s4, 22
	v_writelane_b32 v248, s5, 23
	v_readlane_b32 s4, v249, 46
	v_readlane_b32 s5, v249, 47
	s_nop 1
	v_writelane_b32 v248, s4, 24
	v_writelane_b32 v248, s5, 25
	v_readlane_b32 s4, v249, 48
	v_readlane_b32 s5, v249, 49
	s_nop 1
	v_writelane_b32 v248, s4, 26
	v_writelane_b32 v248, s5, 27
	s_mov_b32 s4, 0
	v_writelane_b32 v248, s4, 28
	v_readlane_b32 s4, v249, 15
	v_readlane_b32 s5, v249, 16
.Lks_done:
	v_mov_b32_e32 v18, v182
	s_andn2_b64 vcc, exec, s[4:5]
	v_readfirstlane_b32 s13, v18
	s_cbranch_vccnz .LBB0_810
	v_lshlrev_b32_e32 v0, 4, v18
	v_add_u32_e32 v1, 0x2000, v0
	v_ashrrev_i32_e32 v2, 31, v1
	v_lshrrev_b32_e32 v2, 22, v2
	v_add_u32_e32 v2, v1, v2
	v_ashrrev_i32_e32 v2, 10, v2
	v_mul_i32_i24_e32 v3, 0x400, v2
	v_sub_u32_e32 v1, v1, v3
	v_lshrrev_b32_e32 v3, 4, v1
	v_bitop3_b32 v1, v3, v1, 32 bitop3:0x6c
	v_ashrrev_i32_e32 v3, 31, v1
	v_lshrrev_b32_e32 v3, 26, v3
	v_add_u32_e32 v3, v1, v3
	v_lshlrev_b32_e32 v5, 3, v2
	v_ashrrev_i32_e32 v4, 6, v3
	v_and_b32_e32 v5, -16, v5
	v_lshlrev_b32_e32 v2, 5, v2
	v_add_u32_e32 v5, v4, v5
	v_and_b32_e32 v12, 32, v2
	v_and_b32_e32 v2, 0xc0, v3
	v_and_b32_e32 v4, 3, v4
	s_mov_b32 s6, 0x7fffffe0
	v_lshrrev_b32_e32 v6, 2, v5
	v_lshlrev_b32_e32 v7, 1, v5
	v_sub_u32_e32 v1, v1, v2
	v_and_or_b32 v4, v5, s6, v4
	v_and_b32_e32 v6, 4, v6
	v_and_b32_e32 v7, 24, v7
	v_ashrrev_i16_sdwa v1, v186, sext(v1) dst_sel:DWORD dst_unused:UNUSED_PAD src0_sel:DWORD src1_sel:BYTE_0
	v_or3_b32 v4, v4, v6, v7
	v_bfe_i32 v13, v1, 0, 16
	v_mul_lo_u32 v4, v4, s12
	v_add_u32_e32 v1, v12, v13
	v_mul_lo_u32 v14, v5, s12
	v_add_lshl_u32 v128, v4, v1, 1
	v_add_lshl_u32 v130, v1, v14, 1
	v_bfe_i32 v1, v18, 27, 1
	v_lshrrev_b32_e32 v1, 22, v1
	v_add_u32_e32 v1, v0, v1
	v_and_b32_e32 v1, 0xfffffc00, v1
	v_sub_u32_e32 v0, v0, v1
	v_lshrrev_b32_e32 v1, 4, v0
	v_ashrrev_i32_e32 v3, 31, v18
	s_lshl_b32 s4, s12, 14
	v_bitop3_b32 v0, v1, v0, 32 bitop3:0x6c
	v_lshrrev_b32_e32 v3, 26, v3
	s_add_u32 s54, s34, s4
	v_ashrrev_i32_e32 v1, 31, v0
	v_add_u32_e32 v3, v18, v3
	v_readlane_b32 s8, v248, 24
	s_addc_u32 s55, s35, 0
	v_lshrrev_b32_e32 v1, 26, v1
	v_ashrrev_i32_e32 v3, 6, v3
	s_movk_i32 s57, 0x400
	v_readlane_b32 s9, v248, 25
	s_mov_b32 s10, s8
	v_add_u32_e32 v1, v0, v1
	v_lshlrev_b32_e32 v4, 3, v3
	s_mul_i32 s9, s10, s57
	v_readlane_b32 s10, v248, 26
	s_ashr_i32 s4, s13, 6
	v_ashrrev_i32_e32 v2, 6, v1
	v_and_b32_e32 v4, -16, v4
	v_readlane_b32 s11, v248, 27
	s_mov_b32 s14, s10
	s_ashr_i32 s5, s13, 8
	s_lshl_b32 s56, s4, 10
	v_add_u32_e32 v4, v2, v4
	v_and_b32_e32 v1, 0xc0, v1
	s_mul_i32 s11, s53, s14
	v_and_b32_e32 v2, 3, v2
	v_lshrrev_b32_e32 v5, 2, v4
	v_lshlrev_b32_e32 v6, 1, v4
	v_sub_u32_e32 v0, v0, v1
	s_mul_hi_i32 s10, s53, s10
	s_add_u32 s11, s18, s11
	v_and_or_b32 v2, v4, s6, v2
	v_and_b32_e32 v5, 4, v5
	v_and_b32_e32 v6, 24, v6
	v_lshlrev_b32_e32 v3, 5, v3
	v_ashrrev_i16_sdwa v0, v186, sext(v0) dst_sel:DWORD dst_unused:UNUSED_PAD src0_sel:DWORD src1_sel:BYTE_0
	s_addc_u32 s10, s52, s10
	v_or3_b32 v2, v2, v5, v6
	v_and_b32_e32 v15, 32, v3
	v_bfe_i32 v16, v0, 0, 16
	s_mul_hi_i32 s8, s8, s57
	s_add_u32 s36, s11, s9
	v_mul_lo_u32 v2, v2, s12
	v_add_u32_e32 v0, v15, v16
	s_addc_u32 s37, s10, s8
	s_add_i32 s66, s56, 0
	v_add_lshl_u32 v144, v2, v0, 1
	v_readlane_b32 s7, v248, 23
	s_add_i32 m0, s66, 0x10000
	s_mul_hi_i32 s6, s53, s7
	s_mul_i32 s7, s53, s7
	global_load_lds_dwordx4 v144, s[36:37]
	s_add_i32 m0, s66, 0x12000
	s_add_u32 s7, s54, s7
	s_addc_u32 s6, s55, s6
	v_mul_lo_u32 v17, v4, s12
	s_add_u32 s34, s7, s9
	v_add_lshl_u32 v132, v0, v17, 1
	global_load_lds_dwordx4 v128, s[36:37]
	s_addc_u32 s35, s6, s8
	s_mov_b32 m0, s66
	s_add_i32 s67, s66, 0x2000
	global_load_lds_dwordx4 v132, s[34:35]
	s_mov_b32 m0, s67
	s_add_u32 s6, s36, s76
	global_load_lds_dwordx4 v130, s[34:35]
	s_addc_u32 s7, s37, 0
	s_add_i32 m0, s66, 0x14000
	v_mov_b32_e32 v129, v145
	global_load_lds_dwordx4 v144, s[6:7]
	s_add_i32 m0, s66, 0x16000
	v_lshl_add_u64 v[8:9], s[6:7], 0, v[144:145]
	v_lshl_add_u64 v[10:11], s[6:7], 0, v[128:129]
	global_load_lds_dwordx4 v128, s[6:7]
	s_add_u32 s6, s34, s76
	s_addc_u32 s7, s35, 0
	s_add_i32 s70, s66, 0x4000
	s_mov_b32 m0, s70
	s_add_i32 s71, s66, 0x6000
	global_load_lds_dwordx4 v132, s[6:7]
	s_mov_b32 m0, s71
	v_mov_b32_e32 v133, v145
	global_load_lds_dwordx4 v130, s[6:7]
	v_mov_b32_e32 v131, v145
	v_lshl_add_u64 v[0:1], s[36:37], 0, v[144:145]
	v_lshl_add_u64 v[2:3], s[36:37], 0, v[128:129]
	v_lshl_add_u64 v[4:5], s[34:35], 0, v[132:133]
	v_lshl_add_u64 v[6:7], s[34:35], 0, v[130:131]
	s_cmp_lg_u32 s5, 1
	s_cbranch_scc1 .LBB0_781
	s_barrier
.LBB0_781:
	v_readlane_b32 s16, v248, 28
	s_cmp_lg_u32 s16, 0
	s_mov_b32 s16, 0x1a3a0000
	s_cselect_b32 s16, 0x13b80000, s16
	s_add_u32 s6, s26, 0x1a5a0000
	s_addc_u32 s7, s27, 0
	s_add_u32 s8, s26, 0x1a7a0000
	s_addc_u32 s9, s27, 0
	v_lshrrev_b32_e32 v20, 1, v18
	s_add_u32 s10, s26, 0x1a9a0000
	v_and_b32_e32 v20, 24, v20
	s_addc_u32 s11, s27, 0
	v_and_b32_e32 v19, 15, v18
	v_lshlrev_b32_e32 v21, 1, v20
	v_lshlrev_b32_e32 v18, 2, v18
	s_lshl_b32 s4, s4, 5
	v_lshl_or_b32 v140, s5, 6, v19
	v_lshl_or_b32 v19, v19, 6, v21
	s_lshl_b32 s5, s5, 13
	v_and_b32_e32 v18, 32, v18
	s_and_b32 s4, s4, 0x60
	s_mov_b32 s12, 8
	v_bitop3_b32 v21, v19, s5, v18 bitop3:0xde
	s_lshl_b32 s5, s4, 7
	s_add_u32 s16, s26, s16
	s_addc_u32 s17, s27, 0
	s_add_i32 m0, s66, 0x18000
	v_lshl_add_u64 v[0:1], v[0:1], 0, s[86:87]
	s_waitcnt vmcnt(4)
	s_barrier
	global_load_lds_dwordx4 v[0:1], off
	v_lshl_add_u64 v[0:1], v[2:3], 0, s[86:87]
	s_add_i32 m0, s66, 0x1a000
	s_add_i32 s72, s66, 0x8000
	global_load_lds_dwordx4 v[0:1], off
	v_lshl_add_u64 v[0:1], v[4:5], 0, s[86:87]
	s_mov_b32 m0, s72
	s_add_i32 s73, s66, 0xa000
	global_load_lds_dwordx4 v[0:1], off
	v_lshl_add_u64 v[0:1], v[6:7], 0, s[86:87]
	s_mov_b32 m0, s73
	v_bitop3_b32 v141, v19, s5, v18 bitop3:0xde
	global_load_lds_dwordx4 v[0:1], off
	s_add_i32 m0, s66, 0x1c000
	v_lshl_add_u64 v[0:1], v[8:9], 0, s[86:87]
	global_load_lds_dwordx4 v[0:1], off
	v_lshl_add_u64 v[0:1], v[10:11], 0, s[86:87]
	s_add_i32 m0, s66, 0x1e000
	s_add_i32 s74, s12, -2
	global_load_lds_dwordx4 v[0:1], off
	v_add_u32_e32 v0, v17, v15
	v_add_lshl_u32 v0, v0, v16, 1
	v_mov_b32_e32 v1, v145
	s_waitcnt vmcnt(6)
	v_lshl_add_u64 v[134:135], s[76:77], 0, v[0:1]
	v_add_u32_e32 v0, v14, v12
	v_add_lshl_u32 v0, v0, v13, 1
	v_or_b32_e32 v142, s4, v20
	v_lshl_add_u64 v[136:137], s[76:77], 0, v[0:1]
	s_mov_b32 s75, 0
	v_add_u32_e32 v143, 0, v21
	v_readlane_b32 s88, v248, 22
	v_readlane_b32 s89, v248, 23
	s_barrier
	s_branch .LBB0_783

.LBB0_794:
	s_add_i32 vcc_lo, s36, 2
	s_add_u32 s50, s34, 0x80
	s_addc_u32 s37, s35, 0
	s_add_i32 vcc_hi, 0, 0x10000
	v_add_u32_e32 v138, vcc_hi, v141
	ds_read_b128 v[162:165], v138
	ds_read_b128 v[166:169], v138 offset:1024
	ds_read_b128 v[170:173], v138 offset:2048
	ds_read_b128 v[174:177], v138 offset:3072
	s_cmp_eq_u32 s74, s36
	s_cselect_b32 s36, s30, s50
	s_cselect_b32 s37, s31, s37
	s_cselect_b32 s51, s5, s95
	s_cselect_b32 s50, s4, s94
	v_lshl_add_u64 v[138:139], s[34:35], 0, v[134:135]
	s_add_i32 m0, s66, 0xc000
	ds_read_b128 v[178:181], v143
	ds_read_b128 v[194:197], v143 offset:1024
	ds_read_b128 v[198:201], v143 offset:2048
	ds_read_b128 v[202:205], v143 offset:3072
	ds_read_b128 v[206:209], v143 offset:4096
	ds_read_b128 v[210:213], v143 offset:5120
	ds_read_b128 v[214:217], v143 offset:6144
	ds_read_b128 v[218:221], v143 offset:7168
	global_load_lds_dwordx4 v[138:139], off
	v_lshl_add_u64 v[138:139], s[34:35], 0, v[136:137]
	s_add_i32 m0, s66, 0xe000
	s_nop 0
	global_load_lds_dwordx4 v[138:139], off
	s_waitcnt lgkmcnt(8)
	s_barrier
	s_waitcnt lgkmcnt(0)
	s_setprio 1
	s_waitcnt lgkmcnt(0)
	v_mfma_f32_16x16x32_bf16 v[124:127], v[162:165], v[178:181], v[124:127]
	v_mfma_f32_16x16x32_bf16 v[120:123], v[170:173], v[178:181], v[120:123]
	v_mfma_f32_16x16x32_bf16 v[116:119], v[162:165], v[198:201], v[116:119]
	v_mfma_f32_16x16x32_bf16 v[108:111], v[170:173], v[198:201], v[108:111]
	v_mfma_f32_16x16x32_bf16 v[100:103], v[162:165], v[206:209], v[100:103]
	v_mfma_f32_16x16x32_bf16 v[92:95], v[170:173], v[206:209], v[92:95]
	v_mfma_f32_16x16x32_bf16 v[84:87], v[162:165], v[214:217], v[84:87]
	v_mfma_f32_16x16x32_bf16 v[76:79], v[170:173], v[214:217], v[76:79]
	v_mfma_f32_16x16x32_bf16 v[124:127], v[166:169], v[194:197], v[124:127]
	v_mfma_f32_16x16x32_bf16 v[120:123], v[174:177], v[194:197], v[120:123]
	v_mfma_f32_16x16x32_bf16 v[116:119], v[166:169], v[202:205], v[116:119]
	v_mfma_f32_16x16x32_bf16 v[108:111], v[174:177], v[202:205], v[108:111]
	v_mfma_f32_16x16x32_bf16 v[100:103], v[166:169], v[210:213], v[100:103]
	v_mfma_f32_16x16x32_bf16 v[92:95], v[174:177], v[210:213], v[92:95]
	v_mfma_f32_16x16x32_bf16 v[84:87], v[166:169], v[218:221], v[84:87]
	v_mfma_f32_16x16x32_bf16 v[76:79], v[174:177], v[218:221], v[76:79]
	s_setprio 0
	s_barrier
	s_add_i32 s14, 0, 0x14000
	v_add_u32_e32 v138, s14, v141
	s_add_i32 s15, vcc_hi, s56
	ds_read_b128 v[222:225], v138
	ds_read_b128 v[226:229], v138 offset:1024
	ds_read_b128 v[230:233], v138 offset:2048
	ds_read_b128 v[234:237], v138 offset:3072
	v_lshl_add_u64 v[138:139], s[50:51], 0, v[144:145]
	s_mov_b32 m0, s15
	v_lshl_add_u64 v[238:239], s[50:51], 0, v[128:129]
	global_load_lds_dwordx4 v[138:139], off
	s_add_i32 m0, s15, 0x2000
	s_nop 0
	global_load_lds_dwordx4 v[238:239], off
	s_barrier
	s_waitcnt lgkmcnt(0)
	s_setprio 1
	s_waitcnt lgkmcnt(0)
	v_mfma_f32_16x16x32_bf16 v[112:115], v[222:225], v[178:181], v[112:115]
	v_mfma_f32_16x16x32_bf16 v[104:107], v[230:233], v[178:181], v[104:107]
	v_mfma_f32_16x16x32_bf16 v[96:99], v[222:225], v[198:201], v[96:99]
	v_mfma_f32_16x16x32_bf16 v[88:91], v[230:233], v[198:201], v[88:91]
	v_mfma_f32_16x16x32_bf16 v[80:83], v[222:225], v[206:209], v[80:83]
	v_mfma_f32_16x16x32_bf16 v[72:75], v[230:233], v[206:209], v[72:75]
	v_mfma_f32_16x16x32_bf16 v[68:71], v[222:225], v[214:217], v[68:71]
	v_mfma_f32_16x16x32_bf16 v[64:67], v[230:233], v[214:217], v[64:67]
	v_mfma_f32_16x16x32_bf16 v[112:115], v[226:229], v[194:197], v[112:115]
	v_mfma_f32_16x16x32_bf16 v[104:107], v[234:237], v[194:197], v[104:107]
	v_mfma_f32_16x16x32_bf16 v[96:99], v[226:229], v[202:205], v[96:99]
	v_mfma_f32_16x16x32_bf16 v[88:91], v[234:237], v[202:205], v[88:91]
	v_mfma_f32_16x16x32_bf16 v[80:83], v[226:229], v[210:213], v[80:83]
	v_mfma_f32_16x16x32_bf16 v[72:75], v[234:237], v[210:213], v[72:75]
	v_mfma_f32_16x16x32_bf16 v[68:71], v[226:229], v[218:221], v[68:71]
	v_mfma_f32_16x16x32_bf16 v[64:67], v[234:237], v[218:221], v[64:67]
	s_setprio 0
	s_mov_b32 m0, s66
	v_lshl_add_u64 v[240:241], s[36:37], 0, v[132:133]
	s_barrier
	ds_read_b128 v[178:181], v143 offset:16384
	ds_read_b128 v[194:197], v143 offset:17408
	ds_read_b128 v[198:201], v143 offset:18432
	ds_read_b128 v[202:205], v143 offset:19456
	ds_read_b128 v[206:209], v143 offset:20480
	ds_read_b128 v[210:213], v143 offset:21504
	ds_read_b128 v[214:217], v143 offset:22528
	ds_read_b128 v[218:221], v143 offset:23552
	global_load_lds_dwordx4 v[240:241], off
	v_lshl_add_u64 v[242:243], s[36:37], 0, v[130:131]
	s_mov_b32 m0, s67
	s_nop 0
	global_load_lds_dwordx4 v[242:243], off
	s_barrier
	s_waitcnt lgkmcnt(0)
	s_setprio 1
	s_waitcnt lgkmcnt(0)
	v_mfma_f32_16x16x32_bf16 v[60:63], v[162:165], v[178:181], v[60:63]
	v_mfma_f32_16x16x32_bf16 v[56:59], v[170:173], v[178:181], v[56:59]
	v_mfma_f32_16x16x32_bf16 v[52:55], v[162:165], v[198:201], v[52:55]
	v_mfma_f32_16x16x32_bf16 v[48:51], v[170:173], v[198:201], v[48:51]
	v_mfma_f32_16x16x32_bf16 v[36:39], v[162:165], v[206:209], v[36:39]
	v_mfma_f32_16x16x32_bf16 v[32:35], v[170:173], v[206:209], v[32:35]
	v_mfma_f32_16x16x32_bf16 v[20:23], v[162:165], v[214:217], v[20:23]
	v_mfma_f32_16x16x32_bf16 v[16:19], v[170:173], v[214:217], v[16:19]
	v_mfma_f32_16x16x32_bf16 v[60:63], v[166:169], v[194:197], v[60:63]
	v_mfma_f32_16x16x32_bf16 v[56:59], v[174:177], v[194:197], v[56:59]
	v_mfma_f32_16x16x32_bf16 v[52:55], v[166:169], v[202:205], v[52:55]
	v_mfma_f32_16x16x32_bf16 v[48:51], v[174:177], v[202:205], v[48:51]
	v_mfma_f32_16x16x32_bf16 v[36:39], v[166:169], v[210:213], v[36:39]
	v_mfma_f32_16x16x32_bf16 v[32:35], v[174:177], v[210:213], v[32:35]
	v_mfma_f32_16x16x32_bf16 v[20:23], v[166:169], v[218:221], v[20:23]
	v_mfma_f32_16x16x32_bf16 v[16:19], v[174:177], v[218:221], v[16:19]
	s_setprio 0
	s_barrier
	s_add_u32 s50, s50, s76
	s_addc_u32 s51, s51, 0
	s_add_i32 s14, s14, s56
	v_lshl_add_u64 v[244:245], s[50:51], 0, v[144:145]
	s_mov_b32 m0, s14
	v_lshl_add_u64 v[246:247], s[50:51], 0, v[128:129]
	global_load_lds_dwordx4 v[244:245], off
	s_add_i32 m0, s14, 0x2000
	s_nop 0
	global_load_lds_dwordx4 v[246:247], off
	s_waitcnt vmcnt(6)
	s_barrier
	s_setprio 1
	v_mfma_f32_16x16x32_bf16 v[44:47], v[222:225], v[178:181], v[44:47]
	v_mfma_f32_16x16x32_bf16 v[40:43], v[230:233], v[178:181], v[40:43]
	v_mfma_f32_16x16x32_bf16 v[28:31], v[222:225], v[198:201], v[28:31]
	v_mfma_f32_16x16x32_bf16 v[24:27], v[230:233], v[198:201], v[24:27]
	v_mfma_f32_16x16x32_bf16 v[12:15], v[222:225], v[206:209], v[12:15]
	v_mfma_f32_16x16x32_bf16 v[8:11], v[230:233], v[206:209], v[8:11]
	v_mfma_f32_16x16x32_bf16 v[4:7], v[222:225], v[214:217], v[4:7]
	v_mfma_f32_16x16x32_bf16 v[0:3], v[230:233], v[214:217], v[0:3]
	v_mfma_f32_16x16x32_bf16 v[44:47], v[226:229], v[194:197], v[44:47]
	v_mfma_f32_16x16x32_bf16 v[40:43], v[234:237], v[194:197], v[40:43]
	v_mfma_f32_16x16x32_bf16 v[28:31], v[226:229], v[202:205], v[28:31]
	v_mfma_f32_16x16x32_bf16 v[24:27], v[234:237], v[202:205], v[24:27]
	v_mfma_f32_16x16x32_bf16 v[12:15], v[226:229], v[210:213], v[12:15]
	v_mfma_f32_16x16x32_bf16 v[8:11], v[234:237], v[210:213], v[8:11]
	v_mfma_f32_16x16x32_bf16 v[4:7], v[226:229], v[218:221], v[4:7]
	v_mfma_f32_16x16x32_bf16 v[0:3], v[234:237], v[218:221], v[0:3]
	s_setprio 0
	s_add_i32 s14, 0, 0x18000
	v_add_u32_e32 v174, s14, v141
	s_barrier
	ds_read_b128 v[162:165], v174
	ds_read_b128 v[166:169], v174 offset:1024
	ds_read_b128 v[170:173], v174 offset:2048
	ds_read_b128 v[174:177], v174 offset:3072
	s_add_u32 s36, s36, s76
	s_addc_u32 s37, s37, 0
	s_mov_b32 m0, s70
	v_lshl_add_u64 v[222:223], s[36:37], 0, v[132:133]
	ds_read_b128 v[178:181], v143 offset:32768
	ds_read_b128 v[194:197], v143 offset:33792
	ds_read_b128 v[198:201], v143 offset:34816
	ds_read_b128 v[202:205], v143 offset:35840
	ds_read_b128 v[206:209], v143 offset:36864
	ds_read_b128 v[210:213], v143 offset:37888
	ds_read_b128 v[214:217], v143 offset:38912
	ds_read_b128 v[218:221], v143 offset:39936
	global_load_lds_dwordx4 v[222:223], off
	v_lshl_add_u64 v[222:223], s[36:37], 0, v[130:131]
	s_mov_b32 m0, s71
	s_nop 0
	global_load_lds_dwordx4 v[222:223], off
	s_waitcnt lgkmcnt(8)
	s_barrier
	s_waitcnt lgkmcnt(0)
	s_setprio 1
	s_waitcnt lgkmcnt(0)
	v_mfma_f32_16x16x32_bf16 v[124:127], v[162:165], v[178:181], v[124:127]
	v_mfma_f32_16x16x32_bf16 v[120:123], v[170:173], v[178:181], v[120:123]
	v_mfma_f32_16x16x32_bf16 v[116:119], v[162:165], v[198:201], v[116:119]
	v_mfma_f32_16x16x32_bf16 v[108:111], v[170:173], v[198:201], v[108:111]
	v_mfma_f32_16x16x32_bf16 v[100:103], v[162:165], v[206:209], v[100:103]
	v_mfma_f32_16x16x32_bf16 v[92:95], v[170:173], v[206:209], v[92:95]
	v_mfma_f32_16x16x32_bf16 v[84:87], v[162:165], v[214:217], v[84:87]
	v_mfma_f32_16x16x32_bf16 v[76:79], v[170:173], v[214:217], v[76:79]
	v_mfma_f32_16x16x32_bf16 v[124:127], v[166:169], v[194:197], v[124:127]
	v_mfma_f32_16x16x32_bf16 v[120:123], v[174:177], v[194:197], v[120:123]
	v_mfma_f32_16x16x32_bf16 v[116:119], v[166:169], v[202:205], v[116:119]
	v_mfma_f32_16x16x32_bf16 v[108:111], v[174:177], v[202:205], v[108:111]
	v_mfma_f32_16x16x32_bf16 v[100:103], v[166:169], v[210:213], v[100:103]
	v_mfma_f32_16x16x32_bf16 v[92:95], v[174:177], v[210:213], v[92:95]
	v_mfma_f32_16x16x32_bf16 v[84:87], v[166:169], v[218:221], v[84:87]
	v_mfma_f32_16x16x32_bf16 v[76:79], v[174:177], v[218:221], v[76:79]
	s_setprio 0
	s_barrier
	s_add_i32 s15, 0, 0x1c000
	s_add_i32 s14, s14, s56
	v_add_u32_e32 v193, s15, v141
	v_lshl_add_u64 v[138:139], v[138:139], 0, s[86:87]
	s_mov_b32 m0, s14
	ds_read_b128 v[222:225], v193
	ds_read_b128 v[226:229], v193 offset:1024
	ds_read_b128 v[230:233], v193 offset:2048
	ds_read_b128 v[234:237], v193 offset:3072
	global_load_lds_dwordx4 v[138:139], off
	v_lshl_add_u64 v[138:139], v[238:239], 0, s[86:87]
	s_add_i32 m0, s14, 0x2000
	s_nop 0
	global_load_lds_dwordx4 v[138:139], off
	s_barrier
	s_waitcnt lgkmcnt(0)
	s_setprio 1
	s_waitcnt lgkmcnt(0)
	v_mfma_f32_16x16x32_bf16 v[112:115], v[222:225], v[178:181], v[112:115]
	v_mfma_f32_16x16x32_bf16 v[104:107], v[230:233], v[178:181], v[104:107]
	v_mfma_f32_16x16x32_bf16 v[96:99], v[222:225], v[198:201], v[96:99]
	v_mfma_f32_16x16x32_bf16 v[88:91], v[230:233], v[198:201], v[88:91]
	v_mfma_f32_16x16x32_bf16 v[80:83], v[222:225], v[206:209], v[80:83]
	v_mfma_f32_16x16x32_bf16 v[72:75], v[230:233], v[206:209], v[72:75]
	v_mfma_f32_16x16x32_bf16 v[68:71], v[222:225], v[214:217], v[68:71]
	v_mfma_f32_16x16x32_bf16 v[64:67], v[230:233], v[214:217], v[64:67]
	v_mfma_f32_16x16x32_bf16 v[112:115], v[226:229], v[194:197], v[112:115]
	v_mfma_f32_16x16x32_bf16 v[104:107], v[234:237], v[194:197], v[104:107]
	v_mfma_f32_16x16x32_bf16 v[96:99], v[226:229], v[202:205], v[96:99]
	v_mfma_f32_16x16x32_bf16 v[88:91], v[234:237], v[202:205], v[88:91]
	v_mfma_f32_16x16x32_bf16 v[80:83], v[226:229], v[210:213], v[80:83]
	v_mfma_f32_16x16x32_bf16 v[72:75], v[234:237], v[210:213], v[72:75]
	v_mfma_f32_16x16x32_bf16 v[68:71], v[226:229], v[218:221], v[68:71]
	v_mfma_f32_16x16x32_bf16 v[64:67], v[234:237], v[218:221], v[64:67]
	s_setprio 0
	s_mov_b32 m0, s72
	v_lshl_add_u64 v[138:139], v[240:241], 0, s[86:87]
	s_barrier
	ds_read_b128 v[178:181], v143 offset:49152
	ds_read_b128 v[194:197], v143 offset:50176
	ds_read_b128 v[198:201], v143 offset:51200
	ds_read_b128 v[202:205], v143 offset:52224
	ds_read_b128 v[206:209], v143 offset:53248
	ds_read_b128 v[210:213], v143 offset:54272
	ds_read_b128 v[214:217], v143 offset:55296
	ds_read_b128 v[218:221], v143 offset:56320
	global_load_lds_dwordx4 v[138:139], off
	v_lshl_add_u64 v[138:139], v[242:243], 0, s[86:87]
	s_mov_b32 m0, s73
	s_nop 0
	global_load_lds_dwordx4 v[138:139], off
	s_barrier
	s_waitcnt lgkmcnt(0)
	s_setprio 1
	s_waitcnt lgkmcnt(0)
	v_mfma_f32_16x16x32_bf16 v[60:63], v[162:165], v[178:181], v[60:63]
	v_mfma_f32_16x16x32_bf16 v[56:59], v[170:173], v[178:181], v[56:59]
	v_mfma_f32_16x16x32_bf16 v[52:55], v[162:165], v[198:201], v[52:55]
	v_mfma_f32_16x16x32_bf16 v[48:51], v[170:173], v[198:201], v[48:51]
	v_mfma_f32_16x16x32_bf16 v[36:39], v[162:165], v[206:209], v[36:39]
	v_mfma_f32_16x16x32_bf16 v[32:35], v[170:173], v[206:209], v[32:35]
	v_mfma_f32_16x16x32_bf16 v[20:23], v[162:165], v[214:217], v[20:23]
	v_mfma_f32_16x16x32_bf16 v[16:19], v[170:173], v[214:217], v[16:19]
	v_mfma_f32_16x16x32_bf16 v[60:63], v[166:169], v[194:197], v[60:63]
	v_mfma_f32_16x16x32_bf16 v[56:59], v[174:177], v[194:197], v[56:59]
	v_mfma_f32_16x16x32_bf16 v[52:55], v[166:169], v[202:205], v[52:55]
	v_mfma_f32_16x16x32_bf16 v[48:51], v[174:177], v[202:205], v[48:51]
	v_mfma_f32_16x16x32_bf16 v[36:39], v[166:169], v[210:213], v[36:39]
	v_mfma_f32_16x16x32_bf16 v[32:35], v[174:177], v[210:213], v[32:35]
	v_mfma_f32_16x16x32_bf16 v[20:23], v[166:169], v[218:221], v[20:23]
	v_mfma_f32_16x16x32_bf16 v[16:19], v[174:177], v[218:221], v[16:19]
	s_setprio 0
	s_barrier
	s_add_i32 s14, s15, s56
	v_lshl_add_u64 v[138:139], v[244:245], 0, s[86:87]
	s_mov_b32 m0, s14
	s_nop 0
	global_load_lds_dwordx4 v[138:139], off
	v_lshl_add_u64 v[138:139], v[246:247], 0, s[86:87]
	s_add_i32 m0, s14, 0x2000
	s_nop 0
	global_load_lds_dwordx4 v[138:139], off
	s_waitcnt vmcnt(6)
	s_barrier
	s_setprio 1
	v_mfma_f32_16x16x32_bf16 v[44:47], v[222:225], v[178:181], v[44:47]
	v_mfma_f32_16x16x32_bf16 v[40:43], v[230:233], v[178:181], v[40:43]
	v_mfma_f32_16x16x32_bf16 v[28:31], v[222:225], v[198:201], v[28:31]
	v_mfma_f32_16x16x32_bf16 v[24:27], v[230:233], v[198:201], v[24:27]
	v_mfma_f32_16x16x32_bf16 v[12:15], v[222:225], v[206:209], v[12:15]
	v_mfma_f32_16x16x32_bf16 v[8:11], v[230:233], v[206:209], v[8:11]
	v_mfma_f32_16x16x32_bf16 v[4:7], v[222:225], v[214:217], v[4:7]
	v_mfma_f32_16x16x32_bf16 v[0:3], v[230:233], v[214:217], v[0:3]
	v_mfma_f32_16x16x32_bf16 v[44:47], v[226:229], v[194:197], v[44:47]
	v_mfma_f32_16x16x32_bf16 v[40:43], v[234:237], v[194:197], v[40:43]
	v_mfma_f32_16x16x32_bf16 v[28:31], v[226:229], v[202:205], v[28:31]
	v_mfma_f32_16x16x32_bf16 v[24:27], v[234:237], v[202:205], v[24:27]
	v_mfma_f32_16x16x32_bf16 v[12:15], v[226:229], v[210:213], v[12:15]
	v_mfma_f32_16x16x32_bf16 v[8:11], v[234:237], v[210:213], v[8:11]
	v_mfma_f32_16x16x32_bf16 v[4:7], v[226:229], v[218:221], v[4:7]
	v_mfma_f32_16x16x32_bf16 v[0:3], v[234:237], v[218:221], v[0:3]
	s_setprio 0
	s_add_u32 s34, s34, 0x100
	s_addc_u32 s35, s35, 0
	s_add_u32 s94, s94, 0x100
	s_addc_u32 s95, s95, 0
	s_cmp_ge_u32 vcc_lo, s12
	s_mov_b32 s36, vcc_lo
	s_barrier
	s_cbranch_scc0 .LBB0_794
	s_ashr_i32 s34, s88, 31
	s_lshr_b32 s34, s34, 29
	s_add_i32 s34, s88, s34
	s_ashr_i32 s94, s34, 3
	s_lshl_b32 s34, s94, 21
	s_add_u32 s36, s16, s34
	s_addc_u32 s37, s17, 0
	s_branch .LBB0_782

.Lrn_ks11:
	v_add_u32_e32 v42, 0x13b80000, v16
	global_load_dwordx4 v[44:47], v42, s[8:9] nt
	v_add_u32_e32 v43, 0x200000, v42
	global_load_dwordx4 v[48:51], v43, s[8:9] nt
	v_add_u32_e32 v43, 0x400000, v42
	global_load_dwordx4 v[52:55], v43, s[8:9] nt
	v_add_u32_e32 v43, 0x600000, v42
	global_load_dwordx4 v[56:59], v43, s[8:9] nt
	v_add_u32_e32 v43, 0x800000, v42
	global_load_dwordx4 v[60:63], v43, s[8:9] nt
	v_add_u32_e32 v43, 0xa00000, v42
	global_load_dwordx4 v[64:67], v43, s[8:9] nt
	v_add_u32_e32 v43, 0xc00000, v42
	global_load_dwordx4 v[68:71], v43, s[8:9] nt
	v_add_u32_e32 v43, 0xe00000, v42
	global_load_dwordx4 v[72:75], v43, s[8:9] nt
	v_add_u32_e32 v43, 0x1000000, v42
	global_load_dwordx4 v[76:79], v43, s[8:9] nt
	v_add_u32_e32 v43, 0x1200000, v42
	global_load_dwordx4 v[80:83], v43, s[8:9] nt
	v_add_u32_e32 v43, 0x1400000, v42
	global_load_dwordx4 v[84:87], v43, s[8:9] nt
	v_and_b32_e32 v21, 64, v189
	v_xor_b32_e32 v30, 1, v189
	v_add_u32_e32 v40, 64, v21
	v_cmp_lt_i32_e32 vcc, v30, v40
	s_bfe_u32 s12, s18, 0x30006
	v_cmp_eq_u32_e64 s[4:5], 0, v180
	v_cndmask_b32_e32 v21, v189, v30, vcc
	v_lshlrev_b32_e32 v21, 2, v21
	s_waitcnt lgkmcnt(0)
	s_barrier
	s_waitcnt vmcnt(0)
	v_lshlrev_b32_e32 v12, 16, v44
	v_and_b32_e32 v13, 0xffff0000, v44
	v_lshlrev_b32_e32 v14, 16, v45
	v_and_b32_e32 v15, 0xffff0000, v45
	v_lshlrev_b32_e32 v16, 16, v46
	v_and_b32_e32 v17, 0xffff0000, v46
	v_lshlrev_b32_e32 v18, 16, v47
	v_and_b32_e32 v19, 0xffff0000, v47
	v_lshlrev_b32_e32 v88, 16, v48
	v_and_b32_e32 v89, 0xffff0000, v48
	v_pk_add_f32 v[12:13], v[12:13], v[88:89]
	v_lshlrev_b32_e32 v88, 16, v49
	v_and_b32_e32 v89, 0xffff0000, v49
	v_pk_add_f32 v[14:15], v[14:15], v[88:89]
	v_lshlrev_b32_e32 v88, 16, v50
	v_and_b32_e32 v89, 0xffff0000, v50
	v_pk_add_f32 v[16:17], v[16:17], v[88:89]
	v_lshlrev_b32_e32 v88, 16, v51
	v_and_b32_e32 v89, 0xffff0000, v51
	v_pk_add_f32 v[18:19], v[18:19], v[88:89]
	v_lshlrev_b32_e32 v88, 16, v52
	v_and_b32_e32 v89, 0xffff0000, v52
	v_pk_add_f32 v[12:13], v[12:13], v[88:89]
	v_lshlrev_b32_e32 v88, 16, v53
	v_and_b32_e32 v89, 0xffff0000, v53
	v_pk_add_f32 v[14:15], v[14:15], v[88:89]
	v_lshlrev_b32_e32 v88, 16, v54
	v_and_b32_e32 v89, 0xffff0000, v54
	v_pk_add_f32 v[16:17], v[16:17], v[88:89]
	v_lshlrev_b32_e32 v88, 16, v55
	v_and_b32_e32 v89, 0xffff0000, v55
	v_pk_add_f32 v[18:19], v[18:19], v[88:89]
	v_lshlrev_b32_e32 v88, 16, v56
	v_and_b32_e32 v89, 0xffff0000, v56
	v_pk_add_f32 v[12:13], v[12:13], v[88:89]
	v_lshlrev_b32_e32 v88, 16, v57
	v_and_b32_e32 v89, 0xffff0000, v57
	v_pk_add_f32 v[14:15], v[14:15], v[88:89]
	v_lshlrev_b32_e32 v88, 16, v58
	v_and_b32_e32 v89, 0xffff0000, v58
	v_pk_add_f32 v[16:17], v[16:17], v[88:89]
	v_lshlrev_b32_e32 v88, 16, v59
	v_and_b32_e32 v89, 0xffff0000, v59
	v_pk_add_f32 v[18:19], v[18:19], v[88:89]
	v_lshlrev_b32_e32 v88, 16, v60
	v_and_b32_e32 v89, 0xffff0000, v60
	v_pk_add_f32 v[12:13], v[12:13], v[88:89]
	v_lshlrev_b32_e32 v88, 16, v61
	v_and_b32_e32 v89, 0xffff0000, v61
	v_pk_add_f32 v[14:15], v[14:15], v[88:89]
	v_lshlrev_b32_e32 v88, 16, v62
	v_and_b32_e32 v89, 0xffff0000, v62
	v_pk_add_f32 v[16:17], v[16:17], v[88:89]
	v_lshlrev_b32_e32 v88, 16, v63
	v_and_b32_e32 v89, 0xffff0000, v63
	v_pk_add_f32 v[18:19], v[18:19], v[88:89]
	v_lshlrev_b32_e32 v88, 16, v64
	v_and_b32_e32 v89, 0xffff0000, v64
	v_pk_add_f32 v[12:13], v[12:13], v[88:89]
	v_lshlrev_b32_e32 v88, 16, v65
	v_and_b32_e32 v89, 0xffff0000, v65
	v_pk_add_f32 v[14:15], v[14:15], v[88:89]
	v_lshlrev_b32_e32 v88, 16, v66
	v_and_b32_e32 v89, 0xffff0000, v66
	v_pk_add_f32 v[16:17], v[16:17], v[88:89]
	v_lshlrev_b32_e32 v88, 16, v67
	v_and_b32_e32 v89, 0xffff0000, v67
	v_pk_add_f32 v[18:19], v[18:19], v[88:89]
	v_lshlrev_b32_e32 v88, 16, v68
	v_and_b32_e32 v89, 0xffff0000, v68
	v_pk_add_f32 v[12:13], v[12:13], v[88:89]
	v_lshlrev_b32_e32 v88, 16, v69
	v_and_b32_e32 v89, 0xffff0000, v69
	v_pk_add_f32 v[14:15], v[14:15], v[88:89]
	v_lshlrev_b32_e32 v88, 16, v70
	v_and_b32_e32 v89, 0xffff0000, v70
	v_pk_add_f32 v[16:17], v[16:17], v[88:89]
	v_lshlrev_b32_e32 v88, 16, v71
	v_and_b32_e32 v89, 0xffff0000, v71
	v_pk_add_f32 v[18:19], v[18:19], v[88:89]
	v_lshlrev_b32_e32 v88, 16, v72
	v_and_b32_e32 v89, 0xffff0000, v72
	v_pk_add_f32 v[12:13], v[12:13], v[88:89]
	v_lshlrev_b32_e32 v88, 16, v73
	v_and_b32_e32 v89, 0xffff0000, v73
	v_pk_add_f32 v[14:15], v[14:15], v[88:89]
	v_lshlrev_b32_e32 v88, 16, v74
	v_and_b32_e32 v89, 0xffff0000, v74
	v_pk_add_f32 v[16:17], v[16:17], v[88:89]
	v_lshlrev_b32_e32 v88, 16, v75
	v_and_b32_e32 v89, 0xffff0000, v75
	v_pk_add_f32 v[18:19], v[18:19], v[88:89]
	v_lshlrev_b32_e32 v88, 16, v76
	v_and_b32_e32 v89, 0xffff0000, v76
	v_pk_add_f32 v[12:13], v[12:13], v[88:89]
	v_lshlrev_b32_e32 v88, 16, v77
	v_and_b32_e32 v89, 0xffff0000, v77
	v_pk_add_f32 v[14:15], v[14:15], v[88:89]
	v_lshlrev_b32_e32 v88, 16, v78
	v_and_b32_e32 v89, 0xffff0000, v78
	v_pk_add_f32 v[16:17], v[16:17], v[88:89]
	v_lshlrev_b32_e32 v88, 16, v79
	v_and_b32_e32 v89, 0xffff0000, v79
	v_pk_add_f32 v[18:19], v[18:19], v[88:89]
	v_lshlrev_b32_e32 v88, 16, v80
	v_and_b32_e32 v89, 0xffff0000, v80
	v_pk_add_f32 v[12:13], v[12:13], v[88:89]
	v_lshlrev_b32_e32 v88, 16, v81
	v_and_b32_e32 v89, 0xffff0000, v81
	v_pk_add_f32 v[14:15], v[14:15], v[88:89]
	v_lshlrev_b32_e32 v88, 16, v82
	v_and_b32_e32 v89, 0xffff0000, v82
	v_pk_add_f32 v[16:17], v[16:17], v[88:89]
	v_lshlrev_b32_e32 v88, 16, v83
	v_and_b32_e32 v89, 0xffff0000, v83
	v_pk_add_f32 v[18:19], v[18:19], v[88:89]
	v_lshlrev_b32_e32 v88, 16, v84
	v_and_b32_e32 v89, 0xffff0000, v84
	v_pk_add_f32 v[12:13], v[12:13], v[88:89]
	v_lshlrev_b32_e32 v88, 16, v85
	v_and_b32_e32 v89, 0xffff0000, v85
	v_pk_add_f32 v[14:15], v[14:15], v[88:89]
	v_lshlrev_b32_e32 v88, 16, v86
	v_and_b32_e32 v89, 0xffff0000, v86
	v_pk_add_f32 v[16:17], v[16:17], v[88:89]
	v_lshlrev_b32_e32 v88, 16, v87
	v_and_b32_e32 v89, 0xffff0000, v87
	v_pk_add_f32 v[18:19], v[18:19], v[88:89]
	s_branch .Lrn_sq

.LBB0_1082:
	s_mov_b32 s4, 0xfe000000
	s_mov_b32 s5, -1
	v_lshl_add_u64 v[16:17], v[8:9], 1, s[4:5]
	v_lshl_add_u64 v[26:27], s[8:9], 0, v[16:17]
	s_and_b64 vcc, exec, s[20:21]
	s_cbranch_vccnz .Lrn_ks11
	s_mov_b32 s4, 0x1a5a0000
	v_lshl_add_u64 v[12:13], s[6:7], 0, v[16:17]
	v_add_co_u32_e32 v16, vcc, s4, v26
	s_mov_b32 s4, 0x1a7a0000
	s_nop 0
	v_addc_co_u32_e32 v17, vcc, 0, v27, vcc
	v_add_co_u32_e32 v22, vcc, s4, v26
	s_mov_b32 s4, 0x1a9a0000
	s_nop 0
	v_addc_co_u32_e32 v23, vcc, 0, v27, vcc
	v_add_co_u32_e32 v26, vcc, s4, v26
	global_load_dwordx4 v[12:15], v[12:13], off nt
	s_nop 0
	v_addc_co_u32_e32 v27, vcc, 0, v27, vcc
	global_load_dwordx4 v[16:19], v[16:17], off nt
	v_and_b32_e32 v21, 64, v189
	global_load_dwordx4 v[22:25], v[22:23], off nt
	v_xor_b32_e32 v30, 1, v189
	global_load_dwordx4 v[26:29], v[26:27], off nt
	v_add_u32_e32 v40, 64, v21
	v_cmp_lt_i32_e32 vcc, v30, v40
	s_bfe_u32 s12, s18, 0x30006
	v_cmp_eq_u32_e64 s[4:5], 0, v180
	v_cndmask_b32_e32 v21, v189, v30, vcc
	v_lshlrev_b32_e32 v21, 2, v21
	s_waitcnt lgkmcnt(0)
	s_barrier
	s_waitcnt vmcnt(3)
	v_lshlrev_b32_e32 v32, 16, v14
	v_and_b32_e32 v33, 0xffff0000, v14
	v_lshlrev_b32_e32 v14, 16, v15
	v_and_b32_e32 v15, 0xffff0000, v15
	s_waitcnt vmcnt(2)
	v_lshlrev_b32_e32 v36, 16, v18
	v_and_b32_e32 v37, 0xffff0000, v18
	v_lshlrev_b32_e32 v18, 16, v19
	v_and_b32_e32 v19, 0xffff0000, v19
	v_lshlrev_b32_e32 v30, 16, v12
	v_and_b32_e32 v31, 0xffff0000, v12
	v_lshlrev_b32_e32 v12, 16, v13
	v_and_b32_e32 v13, 0xffff0000, v13
	v_lshlrev_b32_e32 v34, 16, v16
	v_and_b32_e32 v35, 0xffff0000, v16
	v_lshlrev_b32_e32 v16, 16, v17
	v_and_b32_e32 v17, 0xffff0000, v17
	s_waitcnt vmcnt(1)
	v_lshlrev_b32_e32 v38, 16, v22
	v_and_b32_e32 v39, 0xffff0000, v22
	v_pk_add_f32 v[18:19], v[14:15], v[18:19]
	s_waitcnt vmcnt(0)
	v_lshlrev_b32_e32 v14, 16, v26
	v_and_b32_e32 v15, 0xffff0000, v26
	v_pk_add_f32 v[30:31], v[30:31], v[34:35]
	v_lshlrev_b32_e32 v22, 16, v23
	v_and_b32_e32 v23, 0xffff0000, v23
	v_pk_add_f32 v[16:17], v[12:13], v[16:17]
	v_lshlrev_b32_e32 v12, 16, v24
	v_and_b32_e32 v13, 0xffff0000, v24
	v_lshlrev_b32_e32 v26, 16, v27
	v_and_b32_e32 v27, 0xffff0000, v27
	v_lshlrev_b32_e32 v34, 16, v28
	v_and_b32_e32 v35, 0xffff0000, v28
	v_pk_add_f32 v[14:15], v[38:39], v[14:15]
	v_lshlrev_b32_e32 v24, 16, v25
	v_and_b32_e32 v25, 0xffff0000, v25
	v_lshlrev_b32_e32 v28, 16, v29
	v_and_b32_e32 v29, 0xffff0000, v29
	v_pk_add_f32 v[22:23], v[22:23], v[26:27]
	v_pk_add_f32 v[26:27], v[12:13], v[34:35]
	v_pk_add_f32 v[12:13], v[30:31], v[14:15]
	v_pk_add_f32 v[24:25], v[24:25], v[28:29]
	v_pk_add_f32 v[14:15], v[16:17], v[22:23]
	v_pk_add_f32 v[32:33], v[32:33], v[36:37]
	v_pk_add_f32 v[18:19], v[18:19], v[24:25]
	v_pk_add_f32 v[16:17], v[32:33], v[26:27]
.Lrn_sq:
	v_pk_mul_f32 v[22:23], v[12:13], v[12:13]
	v_pk_mul_f32 v[24:25], v[14:15], v[14:15]
	v_add_f32_e32 v22, v22, v23
	v_add_f32_e32 v22, v24, v22
	v_pk_mul_f32 v[26:27], v[16:17], v[16:17]
	v_add_f32_e32 v22, v25, v22
	v_add_f32_e32 v22, v26, v22
	v_pk_mul_f32 v[28:29], v[18:19], v[18:19]
	v_add_f32_e32 v22, v27, v22
	v_add_f32_e32 v22, v28, v22
	v_add_f32_e32 v23, v29, v22
	ds_bpermute_b32 v24, v21, v23
	v_xor_b32_e32 v22, 2, v189
	v_cmp_lt_i32_e32 vcc, v22, v40
	v_xor_b32_e32 v28, 32, v189
	s_waitcnt lgkmcnt(0)
	v_add_f32_e32 v24, v23, v24
	v_cndmask_b32_e32 v22, v189, v22, vcc
	v_lshlrev_b32_e32 v22, 2, v22
	ds_bpermute_b32 v25, v22, v24
	v_xor_b32_e32 v23, 4, v189
	v_cmp_lt_i32_e32 vcc, v23, v40
	s_waitcnt lgkmcnt(0)
	v_add_f32_e32 v25, v24, v25
	v_cndmask_b32_e32 v23, v189, v23, vcc
	v_lshlrev_b32_e32 v23, 2, v23
	ds_bpermute_b32 v26, v23, v25
	v_xor_b32_e32 v24, 8, v189
	v_cmp_lt_i32_e32 vcc, v24, v40
	s_waitcnt lgkmcnt(0)
	v_add_f32_e32 v26, v25, v26
	v_cndmask_b32_e32 v24, v189, v24, vcc
	v_lshlrev_b32_e32 v24, 2, v24
	ds_bpermute_b32 v27, v24, v26
	v_xor_b32_e32 v25, 16, v189
	v_cmp_lt_i32_e32 vcc, v25, v40
	s_waitcnt lgkmcnt(0)
	v_add_f32_e32 v26, v26, v27
	v_cndmask_b32_e32 v25, v189, v25, vcc
	v_lshlrev_b32_e32 v25, 2, v25
	ds_bpermute_b32 v27, v25, v26
	v_cmp_lt_i32_e32 vcc, v28, v40
	s_waitcnt lgkmcnt(0)
	v_add_f32_e32 v27, v26, v27
	v_cndmask_b32_e32 v28, v189, v28, vcc
	v_lshlrev_b32_e32 v26, 2, v28
	ds_bpermute_b32 v28, v26, v27
	s_and_saveexec_b64 s[6:7], s[4:5]
	s_cbranch_execz .LBB0_1084
	s_lshl_b32 s11, s12, 2
	s_add_i32 s11, s11, 0
	s_waitcnt lgkmcnt(0)
	v_add_f32_e32 v27, v27, v28
	v_mov_b32_e32 v28, s11
	ds_write_b32 v28, v27
